# P1 SwiGLU epilogue hand-written with packed math (without the prologue change)
# speedup vs baseline: 1.0424x; 1.0003x over previous
.LBB0_283:
	s_lshl_b32 s19, s62, 8
	s_add_i32 s19, s19, s77
	s_lshl_b32 s18, s18, 7
	v_or_b32_e32 v154, s19, v148
	s_or_b32 s18, s18, s78
	s_ashr_i32 s19, s19, 8
	s_ashr_i32 s18, s18, 6
	s_mul_i32 s19, s19, 44
	s_add_i32 s34, s19, s18
	s_ashr_i32 s35, s34, 31
	s_lshl_b64 s[34:35], s[34:35], 15
	s_add_u32 s34, s46, s34
	s_addc_u32 s35, s47, s35
	v_lshlrev_b32_e32 v228, 7, v154
	v_and_b32_e32 v228, 0x6780, v228
	v_mov_b32_e32 v229, 0
	v_mov_b32_e32 v232, v146
	v_mov_b32_e32 v233, 0
	v_lshl_add_u64 v[228:229], s[34:35], 0, v[228:229]
	v_lshl_add_u64 v[228:229], v[228:229], 0, v[232:233]
	s_mov_b32 s93, 0
	s_mov_b32 s92, 0x1000
	v_lshl_add_u64 v[234:235], v[228:229], 0, s[92:93]
	s_mov_b32 s92, 0x4000
	v_lshl_add_u64 v[236:237], v[228:229], 0, s[92:93]
	s_mov_b32 s92, 0x5000
	v_lshl_add_u64 v[238:239], v[228:229], 0, s[92:93]
	s_mov_b32 s94, 0xbfb8aa3b
	s_mov_b32 s95, 0xbfb8aa3b
	v_pk_mul_f32 v[176:177], v[124:125], s[94:95]
	v_pk_mul_f32 v[178:179], v[126:127], s[94:95]
	v_pk_mul_f32 v[180:181], v[120:121], s[94:95]
	v_pk_mul_f32 v[182:183], v[122:123], s[94:95]
	v_exp_f32_e32 v176, v176
	v_exp_f32_e32 v177, v177
	v_exp_f32_e32 v178, v178
	v_exp_f32_e32 v179, v179
	v_exp_f32_e32 v180, v180
	v_exp_f32_e32 v181, v181
	v_exp_f32_e32 v182, v182
	v_exp_f32_e32 v183, v183
	v_pk_add_f32 v[176:177], v[176:177], 1.0 op_sel_hi:[1,0]
	v_pk_add_f32 v[178:179], v[178:179], 1.0 op_sel_hi:[1,0]
	v_pk_add_f32 v[180:181], v[180:181], 1.0 op_sel_hi:[1,0]
	v_pk_add_f32 v[182:183], v[182:183], 1.0 op_sel_hi:[1,0]
	v_rcp_f32_e32 v176, v176
	v_rcp_f32_e32 v177, v177
	v_rcp_f32_e32 v178, v178
	v_rcp_f32_e32 v179, v179
	v_rcp_f32_e32 v180, v180
	v_rcp_f32_e32 v181, v181
	v_rcp_f32_e32 v182, v182
	v_rcp_f32_e32 v183, v183
	v_pk_mul_f32 v[124:125], v[124:125], v[176:177]
	v_pk_mul_f32 v[126:127], v[126:127], v[178:179]
	v_pk_mul_f32 v[120:121], v[120:121], v[180:181]
	v_pk_mul_f32 v[122:123], v[122:123], v[182:183]
	v_pk_mul_f32 v[124:125], v[124:125], v[116:117]
	v_pk_mul_f32 v[126:127], v[126:127], v[118:119]
	v_pk_mul_f32 v[120:121], v[120:121], v[112:113]
	v_pk_mul_f32 v[122:123], v[122:123], v[114:115]
	v_cvt_pk_bf16_f32 v184, v124, v125
	v_cvt_pk_bf16_f32 v185, v126, v127
	v_cvt_pk_bf16_f32 v186, v120, v121
	v_cvt_pk_bf16_f32 v187, v122, v123
	global_store_dwordx4 v[228:229], v[184:187], off sc1
	v_pk_mul_f32 v[176:177], v[108:109], s[94:95]
	v_pk_mul_f32 v[178:179], v[110:111], s[94:95]
	v_pk_mul_f32 v[180:181], v[104:105], s[94:95]
	v_pk_mul_f32 v[182:183], v[106:107], s[94:95]
	v_exp_f32_e32 v176, v176
	v_exp_f32_e32 v177, v177
	v_exp_f32_e32 v178, v178
	v_exp_f32_e32 v179, v179
	v_exp_f32_e32 v180, v180
	v_exp_f32_e32 v181, v181
	v_exp_f32_e32 v182, v182
	v_exp_f32_e32 v183, v183
	v_pk_add_f32 v[176:177], v[176:177], 1.0 op_sel_hi:[1,0]
	v_pk_add_f32 v[178:179], v[178:179], 1.0 op_sel_hi:[1,0]
	v_pk_add_f32 v[180:181], v[180:181], 1.0 op_sel_hi:[1,0]
	v_pk_add_f32 v[182:183], v[182:183], 1.0 op_sel_hi:[1,0]
	v_rcp_f32_e32 v176, v176
	v_rcp_f32_e32 v177, v177
	v_rcp_f32_e32 v178, v178
	v_rcp_f32_e32 v179, v179
	v_rcp_f32_e32 v180, v180
	v_rcp_f32_e32 v181, v181
	v_rcp_f32_e32 v182, v182
	v_rcp_f32_e32 v183, v183
	v_pk_mul_f32 v[108:109], v[108:109], v[176:177]
	v_pk_mul_f32 v[110:111], v[110:111], v[178:179]
	v_pk_mul_f32 v[104:105], v[104:105], v[180:181]
	v_pk_mul_f32 v[106:107], v[106:107], v[182:183]
	v_pk_mul_f32 v[108:109], v[108:109], v[100:101]
	v_pk_mul_f32 v[110:111], v[110:111], v[102:103]
	v_pk_mul_f32 v[104:105], v[104:105], v[96:97]
	v_pk_mul_f32 v[106:107], v[106:107], v[98:99]
	v_cvt_pk_bf16_f32 v188, v108, v109
	v_cvt_pk_bf16_f32 v189, v110, v111
	v_cvt_pk_bf16_f32 v190, v104, v105
	v_cvt_pk_bf16_f32 v191, v106, v107
	global_store_dwordx4 v[228:229], v[188:191], off offset:2048 sc1
	v_pk_mul_f32 v[176:177], v[92:93], s[94:95]
	v_pk_mul_f32 v[178:179], v[94:95], s[94:95]
	v_pk_mul_f32 v[180:181], v[88:89], s[94:95]
	v_pk_mul_f32 v[182:183], v[90:91], s[94:95]
	v_exp_f32_e32 v176, v176
	v_exp_f32_e32 v177, v177
	v_exp_f32_e32 v178, v178
	v_exp_f32_e32 v179, v179
	v_exp_f32_e32 v180, v180
	v_exp_f32_e32 v181, v181
	v_exp_f32_e32 v182, v182
	v_exp_f32_e32 v183, v183
	v_pk_add_f32 v[176:177], v[176:177], 1.0 op_sel_hi:[1,0]
	v_pk_add_f32 v[178:179], v[178:179], 1.0 op_sel_hi:[1,0]
	v_pk_add_f32 v[180:181], v[180:181], 1.0 op_sel_hi:[1,0]
	v_pk_add_f32 v[182:183], v[182:183], 1.0 op_sel_hi:[1,0]
	v_rcp_f32_e32 v176, v176
	v_rcp_f32_e32 v177, v177
	v_rcp_f32_e32 v178, v178
	v_rcp_f32_e32 v179, v179
	v_rcp_f32_e32 v180, v180
	v_rcp_f32_e32 v181, v181
	v_rcp_f32_e32 v182, v182
	v_rcp_f32_e32 v183, v183
	v_pk_mul_f32 v[92:93], v[92:93], v[176:177]
	v_pk_mul_f32 v[94:95], v[94:95], v[178:179]
	v_pk_mul_f32 v[88:89], v[88:89], v[180:181]
	v_pk_mul_f32 v[90:91], v[90:91], v[182:183]
	v_pk_mul_f32 v[92:93], v[92:93], v[84:85]
	v_pk_mul_f32 v[94:95], v[94:95], v[86:87]
	v_pk_mul_f32 v[88:89], v[88:89], v[80:81]
	v_pk_mul_f32 v[90:91], v[90:91], v[82:83]
	v_cvt_pk_bf16_f32 v184, v92, v93
	v_cvt_pk_bf16_f32 v185, v94, v95
	v_cvt_pk_bf16_f32 v186, v88, v89
	v_cvt_pk_bf16_f32 v187, v90, v91
	global_store_dwordx4 v[234:235], v[184:187], off sc1
	v_pk_mul_f32 v[176:177], v[76:77], s[94:95]
	v_pk_mul_f32 v[178:179], v[78:79], s[94:95]
	v_pk_mul_f32 v[180:181], v[72:73], s[94:95]
	v_pk_mul_f32 v[182:183], v[74:75], s[94:95]
	v_exp_f32_e32 v176, v176
	v_exp_f32_e32 v177, v177
	v_exp_f32_e32 v178, v178
	v_exp_f32_e32 v179, v179
	v_exp_f32_e32 v180, v180
	v_exp_f32_e32 v181, v181
	v_exp_f32_e32 v182, v182
	v_exp_f32_e32 v183, v183
	v_pk_add_f32 v[176:177], v[176:177], 1.0 op_sel_hi:[1,0]
	v_pk_add_f32 v[178:179], v[178:179], 1.0 op_sel_hi:[1,0]
	v_pk_add_f32 v[180:181], v[180:181], 1.0 op_sel_hi:[1,0]
	v_pk_add_f32 v[182:183], v[182:183], 1.0 op_sel_hi:[1,0]
	v_rcp_f32_e32 v176, v176
	v_rcp_f32_e32 v177, v177
	v_rcp_f32_e32 v178, v178
	v_rcp_f32_e32 v179, v179
	v_rcp_f32_e32 v180, v180
	v_rcp_f32_e32 v181, v181
	v_rcp_f32_e32 v182, v182
	v_rcp_f32_e32 v183, v183
	v_pk_mul_f32 v[76:77], v[76:77], v[176:177]
	v_pk_mul_f32 v[78:79], v[78:79], v[178:179]
	v_pk_mul_f32 v[72:73], v[72:73], v[180:181]
	v_pk_mul_f32 v[74:75], v[74:75], v[182:183]
	v_pk_mul_f32 v[76:77], v[76:77], v[68:69]
	v_pk_mul_f32 v[78:79], v[78:79], v[70:71]
	v_pk_mul_f32 v[72:73], v[72:73], v[64:65]
	v_pk_mul_f32 v[74:75], v[74:75], v[66:67]
	v_cvt_pk_bf16_f32 v188, v76, v77
	v_cvt_pk_bf16_f32 v189, v78, v79
	v_cvt_pk_bf16_f32 v190, v72, v73
	v_cvt_pk_bf16_f32 v191, v74, v75
	global_store_dwordx4 v[234:235], v[188:191], off offset:2048 sc1
	v_pk_mul_f32 v[176:177], v[60:61], s[94:95]
	v_pk_mul_f32 v[178:179], v[62:63], s[94:95]
	v_pk_mul_f32 v[180:181], v[56:57], s[94:95]
	v_pk_mul_f32 v[182:183], v[58:59], s[94:95]
	v_exp_f32_e32 v176, v176
	v_exp_f32_e32 v177, v177
	v_exp_f32_e32 v178, v178
	v_exp_f32_e32 v179, v179
	v_exp_f32_e32 v180, v180
	v_exp_f32_e32 v181, v181
	v_exp_f32_e32 v182, v182
	v_exp_f32_e32 v183, v183
	v_pk_add_f32 v[176:177], v[176:177], 1.0 op_sel_hi:[1,0]
	v_pk_add_f32 v[178:179], v[178:179], 1.0 op_sel_hi:[1,0]
	v_pk_add_f32 v[180:181], v[180:181], 1.0 op_sel_hi:[1,0]
	v_pk_add_f32 v[182:183], v[182:183], 1.0 op_sel_hi:[1,0]
	v_rcp_f32_e32 v176, v176
	v_rcp_f32_e32 v177, v177
	v_rcp_f32_e32 v178, v178
	v_rcp_f32_e32 v179, v179
	v_rcp_f32_e32 v180, v180
	v_rcp_f32_e32 v181, v181
	v_rcp_f32_e32 v182, v182
	v_rcp_f32_e32 v183, v183
	v_pk_mul_f32 v[60:61], v[60:61], v[176:177]
	v_pk_mul_f32 v[62:63], v[62:63], v[178:179]
	v_pk_mul_f32 v[56:57], v[56:57], v[180:181]
	v_pk_mul_f32 v[58:59], v[58:59], v[182:183]
	v_pk_mul_f32 v[60:61], v[60:61], v[52:53]
	v_pk_mul_f32 v[62:63], v[62:63], v[54:55]
	v_pk_mul_f32 v[56:57], v[56:57], v[48:49]
	v_pk_mul_f32 v[58:59], v[58:59], v[50:51]
	v_cvt_pk_bf16_f32 v184, v60, v61
	v_cvt_pk_bf16_f32 v185, v62, v63
	v_cvt_pk_bf16_f32 v186, v56, v57
	v_cvt_pk_bf16_f32 v187, v58, v59
	global_store_dwordx4 v[236:237], v[184:187], off sc1
	v_pk_mul_f32 v[176:177], v[44:45], s[94:95]
	v_pk_mul_f32 v[178:179], v[46:47], s[94:95]
	v_pk_mul_f32 v[180:181], v[40:41], s[94:95]
	v_pk_mul_f32 v[182:183], v[42:43], s[94:95]
	v_exp_f32_e32 v176, v176
	v_exp_f32_e32 v177, v177
	v_exp_f32_e32 v178, v178
	v_exp_f32_e32 v179, v179
	v_exp_f32_e32 v180, v180
	v_exp_f32_e32 v181, v181
	v_exp_f32_e32 v182, v182
	v_exp_f32_e32 v183, v183
	v_pk_add_f32 v[176:177], v[176:177], 1.0 op_sel_hi:[1,0]
	v_pk_add_f32 v[178:179], v[178:179], 1.0 op_sel_hi:[1,0]
	v_pk_add_f32 v[180:181], v[180:181], 1.0 op_sel_hi:[1,0]
	v_pk_add_f32 v[182:183], v[182:183], 1.0 op_sel_hi:[1,0]
	v_rcp_f32_e32 v176, v176
	v_rcp_f32_e32 v177, v177
	v_rcp_f32_e32 v178, v178
	v_rcp_f32_e32 v179, v179
	v_rcp_f32_e32 v180, v180
	v_rcp_f32_e32 v181, v181
	v_rcp_f32_e32 v182, v182
	v_rcp_f32_e32 v183, v183
	v_pk_mul_f32 v[44:45], v[44:45], v[176:177]
	v_pk_mul_f32 v[46:47], v[46:47], v[178:179]
	v_pk_mul_f32 v[40:41], v[40:41], v[180:181]
	v_pk_mul_f32 v[42:43], v[42:43], v[182:183]
	v_pk_mul_f32 v[44:45], v[44:45], v[36:37]
	v_pk_mul_f32 v[46:47], v[46:47], v[38:39]
	v_pk_mul_f32 v[40:41], v[40:41], v[32:33]
	v_pk_mul_f32 v[42:43], v[42:43], v[34:35]
	v_cvt_pk_bf16_f32 v188, v44, v45
	v_cvt_pk_bf16_f32 v189, v46, v47
	v_cvt_pk_bf16_f32 v190, v40, v41
	v_cvt_pk_bf16_f32 v191, v42, v43
	global_store_dwordx4 v[236:237], v[188:191], off offset:2048 sc1
	v_pk_mul_f32 v[176:177], v[28:29], s[94:95]
	v_pk_mul_f32 v[178:179], v[30:31], s[94:95]
	v_pk_mul_f32 v[180:181], v[24:25], s[94:95]
	v_pk_mul_f32 v[182:183], v[26:27], s[94:95]
	v_exp_f32_e32 v176, v176
	v_exp_f32_e32 v177, v177
	v_exp_f32_e32 v178, v178
	v_exp_f32_e32 v179, v179
	v_exp_f32_e32 v180, v180
	v_exp_f32_e32 v181, v181
	v_exp_f32_e32 v182, v182
	v_exp_f32_e32 v183, v183
	v_pk_add_f32 v[176:177], v[176:177], 1.0 op_sel_hi:[1,0]
	v_pk_add_f32 v[178:179], v[178:179], 1.0 op_sel_hi:[1,0]
	v_pk_add_f32 v[180:181], v[180:181], 1.0 op_sel_hi:[1,0]
	v_pk_add_f32 v[182:183], v[182:183], 1.0 op_sel_hi:[1,0]
	v_rcp_f32_e32 v176, v176
	v_rcp_f32_e32 v177, v177
	v_rcp_f32_e32 v178, v178
	v_rcp_f32_e32 v179, v179
	v_rcp_f32_e32 v180, v180
	v_rcp_f32_e32 v181, v181
	v_rcp_f32_e32 v182, v182
	v_rcp_f32_e32 v183, v183
	v_pk_mul_f32 v[28:29], v[28:29], v[176:177]
	v_pk_mul_f32 v[30:31], v[30:31], v[178:179]
	v_pk_mul_f32 v[24:25], v[24:25], v[180:181]
	v_pk_mul_f32 v[26:27], v[26:27], v[182:183]
	v_pk_mul_f32 v[28:29], v[28:29], v[20:21]
	v_pk_mul_f32 v[30:31], v[30:31], v[22:23]
	v_pk_mul_f32 v[24:25], v[24:25], v[16:17]
	v_pk_mul_f32 v[26:27], v[26:27], v[18:19]
	v_cvt_pk_bf16_f32 v184, v28, v29
	v_cvt_pk_bf16_f32 v185, v30, v31
	v_cvt_pk_bf16_f32 v186, v24, v25
	v_cvt_pk_bf16_f32 v187, v26, v27
	global_store_dwordx4 v[238:239], v[184:187], off sc1
	v_pk_mul_f32 v[176:177], v[12:13], s[94:95]
	v_pk_mul_f32 v[178:179], v[14:15], s[94:95]
	v_pk_mul_f32 v[180:181], v[8:9], s[94:95]
	v_pk_mul_f32 v[182:183], v[10:11], s[94:95]
	v_exp_f32_e32 v176, v176
	v_exp_f32_e32 v177, v177
	v_exp_f32_e32 v178, v178
	v_exp_f32_e32 v179, v179
	v_exp_f32_e32 v180, v180
	v_exp_f32_e32 v181, v181
	v_exp_f32_e32 v182, v182
	v_exp_f32_e32 v183, v183
	v_pk_add_f32 v[176:177], v[176:177], 1.0 op_sel_hi:[1,0]
	v_pk_add_f32 v[178:179], v[178:179], 1.0 op_sel_hi:[1,0]
	v_pk_add_f32 v[180:181], v[180:181], 1.0 op_sel_hi:[1,0]
	v_pk_add_f32 v[182:183], v[182:183], 1.0 op_sel_hi:[1,0]
	v_rcp_f32_e32 v176, v176
	v_rcp_f32_e32 v177, v177
	v_rcp_f32_e32 v178, v178
	v_rcp_f32_e32 v179, v179
	v_rcp_f32_e32 v180, v180
	v_rcp_f32_e32 v181, v181
	v_rcp_f32_e32 v182, v182
	v_rcp_f32_e32 v183, v183
	v_pk_mul_f32 v[12:13], v[12:13], v[176:177]
	v_pk_mul_f32 v[14:15], v[14:15], v[178:179]
	v_pk_mul_f32 v[8:9], v[8:9], v[180:181]
	v_pk_mul_f32 v[10:11], v[10:11], v[182:183]
	v_pk_mul_f32 v[12:13], v[12:13], v[4:5]
	v_pk_mul_f32 v[14:15], v[14:15], v[6:7]
	v_pk_mul_f32 v[8:9], v[8:9], v[0:1]
	v_pk_mul_f32 v[10:11], v[10:11], v[2:3]
	v_cvt_pk_bf16_f32 v188, v12, v13
	v_cvt_pk_bf16_f32 v189, v14, v15
	v_cvt_pk_bf16_f32 v190, v8, v9
	v_cvt_pk_bf16_f32 v191, v10, v11
	global_store_dwordx4 v[238:239], v[188:191], off offset:2048 sc1
	s_andn2_b64 vcc, exec, s[0:1]
	s_mov_b64 s[0:1], -1
	s_cbranch_vccnz .LBB0_276
	s_andn2_b64 vcc, exec, s[4:5]
	s_cbranch_vccnz .LBB0_275
	s_barrier
	s_branch .LBB0_275
